# v11: v10 + P0 start gain copies preloaded (2->1 round trips each) + 16 redundant post-barrier lgkmcnt(0) deleted from GEMM K-loops
# speedup vs baseline: 1.0066x; 1.0013x over previous
.LBB0_12:
	s_mov_b64 s[20:21], s[0:1]
	s_mov_b32 s5, 0
	s_load_dwordx4 s[12:15], s[20:21], 0x0
	s_load_dwordx2 s[16:17], s[20:21], 0x10
	s_load_dwordx2 s[18:19], s[20:21], 0x88
	s_mov_b32 s4, 0
	v_mbcnt_lo_u32_b32 v0, -1, s5
	v_mbcnt_hi_u32_b32 v128, -1, v0
	s_nop 0
	v_mbcnt_lo_u32_b32 v0, -1, s4
	v_mbcnt_hi_u32_b32 v0, -1, v0
	v_add_u32_e32 v0, s33, v0
	s_movk_i32 s4, 0x400
	s_nop 0
	v_cmp_gt_i32_e32 vcc, s4, v0
	s_and_saveexec_b64 s[4:5], vcc
	s_cbranch_execz .LBB0_15
	s_load_dwordx2 s[6:7], s[20:21], 0x48
	v_lshl_add_u32 v3, v0, 4, 0
	v_ashrrev_i32_e32 v1, 31, v0
	v_add_u32_e32 v2, 0xfffffe00, v0
	v_add_u32_e32 v3, 0x11000, v3
	s_waitcnt lgkmcnt(0)
	v_lshl_add_u64 v[0:1], v[0:1], 4, s[6:7]
	s_mov_b64 s[6:7], 0
	s_mov_b64 s[8:9], 0x2000
	s_movk_i32 s10, 0x1ff
	v_lshl_add_u64 v[210:211], v[0:1], 0, s[8:9]
	global_load_dwordx4 v[212:215], v[0:1], off
	global_load_dwordx4 v[216:219], v[210:211], off
.LBB0_14:
	s_waitcnt vmcnt(0)
	v_mov_b32_e32 v4, v212
	v_mov_b32_e32 v5, v213
	v_mov_b32_e32 v6, v214
	v_mov_b32_e32 v7, v215
	v_mov_b32_e32 v212, v216
	v_mov_b32_e32 v213, v217
	v_mov_b32_e32 v214, v218
	v_mov_b32_e32 v215, v219
	v_add_u32_e32 v2, 0x200, v2
	v_cmp_lt_i32_e32 vcc, s10, v2
	v_lshl_add_u64 v[0:1], v[0:1], 0, s[8:9]
	s_or_b64 s[6:7], vcc, s[6:7]
	s_nop 0
	ds_write_b128 v3, v[4:7]
	v_add_u32_e32 v3, 0x2000, v3
	s_andn2_b64 exec, exec, s[6:7]
	s_cbranch_execnz .LBB0_14
.LBB0_15:
	s_or_b64 exec, exec, s[4:5]
	s_abs_i32 s65, s64
	v_cvt_f32_u32_e32 v0, s65
	s_waitcnt lgkmcnt(0)
	s_barrier
	v_rcp_iflag_f32_e32 v0, v0
	s_load_dwordx4 s[8:11], s[20:21], 0x68
	s_load_dwordx2 s[22:23], s[20:21], 0x20
	s_sub_i32 s5, 0, s65
	s_movk_i32 s4, 0x400
	v_mul_f32_e32 v0, 0x4f7ffffe, v0
	v_cvt_u32_f32_e32 v1, v0
	v_add_u32_e32 v0, s33, v128
	v_cmp_gt_i32_e32 vcc, s4, v0
	v_readfirstlane_b32 s6, v1
	s_mul_i32 s5, s5, s6
	s_mul_hi_u32 s5, s6, s5
	s_add_i32 s5, s6, s5
	v_writelane_b32 v247, s5, 0
	s_and_saveexec_b64 s[24:25], vcc
	s_cbranch_execz .LBB0_18
	s_load_dwordx4 s[4:7], s[20:21], 0x38
	s_lshl_b32 s26, s3, 10
	v_ashrrev_i32_e32 v1, 31, v0
	s_add_i32 s26, s26, 0
	s_movk_i32 s30, 0x1ff
	s_waitcnt lgkmcnt(0)
	v_mov_b32_e32 v2, s4
	v_mov_b32_e32 v3, s5
	v_lshl_add_u64 v[2:3], v[0:1], 4, v[2:3]
	v_lshl_add_u32 v1, v128, 4, s26
	s_movk_i32 s26, 0xe000
	v_add_u32_e32 v4, 0x17000, v1
	s_mov_b64 s[4:5], 0
	s_movk_i32 s31, 0x200
	v_mov_b32_e32 v1, 0
	s_mov_b32 s27, -1
	s_mov_b64 s[28:29], 0x2000
	v_lshl_add_u64 v[210:211], v[0:1], 4, s[6:7]
	global_load_dwordx4 v[212:215], v[2:3], off
	global_load_dwordx4 v[216:219], v[210:211], off
.LBB0_17:
	v_lshl_add_u64 v[6:7], v[0:1], 4, s[6:7]
	v_lshl_add_u64 v[6:7], v[6:7], 0, s[26:27]
	v_cmp_gt_i32_e32 vcc, s31, v0
	s_nop 1
	v_cndmask_b32_e32 v7, v7, v3, vcc
	v_cndmask_b32_e32 v6, v6, v2, vcc
	s_waitcnt vmcnt(0)
	v_mov_b32_e32 v6, v212
	v_mov_b32_e32 v7, v213
	v_mov_b32_e32 v8, v214
	v_mov_b32_e32 v9, v215
	v_mov_b32_e32 v212, v216
	v_mov_b32_e32 v213, v217
	v_mov_b32_e32 v214, v218
	v_mov_b32_e32 v215, v219
	v_cmp_lt_i32_e32 vcc, s30, v0
	v_add_u32_e32 v0, 0x200, v0
	s_or_b64 s[4:5], vcc, s[4:5]
	v_lshl_add_u64 v[2:3], v[2:3], 0, s[28:29]
	s_nop 0
	ds_write_b128 v4, v[6:9]
	v_add_u32_e32 v4, 0x2000, v4
	s_andn2_b64 exec, exec, s[4:5]
	s_cbranch_execnz .LBB0_17

.LBB0_229:
	ds_read_b128 v[144:147], v149
	ds_read_b128 v[154:157], v149 offset:1024
	ds_read_b128 v[158:161], v149 offset:2048
	ds_read_b128 v[162:165], v149 offset:3072
	ds_read_b128 v[166:169], v150
	ds_read_b128 v[170:173], v150 offset:1024
	ds_read_b128 v[174:177], v150 offset:2048
	ds_read_b128 v[178:181], v150 offset:3072
	s_add_u32 s30, s28, 0xfff00080
	s_addc_u32 s31, s29, -1
	s_cmp_eq_u32 s67, 60
	s_cselect_b32 s37, s21, s31
	s_cselect_b32 s36, s59, s30
	s_cselect_b32 s31, s19, s62
	s_cselect_b32 s30, s60, s61
	v_lshl_add_u64 v[214:215], s[28:29], 0, v[136:137]
	s_add_i32 m0, s27, 0xc000
	ds_read_b128 v[182:185], v151
	ds_read_b128 v[186:189], v151 offset:1024
	ds_read_b128 v[190:193], v151 offset:2048
	ds_read_b128 v[194:197], v151 offset:3072
	ds_read_b128 v[198:201], v151 offset:4096
	ds_read_b128 v[202:205], v151 offset:5120
	ds_read_b128 v[206:209], v151 offset:6144
	ds_read_b128 v[210:213], v151 offset:7168
	global_load_lds_dwordx4 v[214:215], off
	v_lshl_add_u64 v[214:215], s[28:29], 0, v[138:139]
	s_add_i32 m0, s27, 0xe000
	s_nop 0
	global_load_lds_dwordx4 v[214:215], off
	s_waitcnt vmcnt(8)
	s_waitcnt lgkmcnt(0)
	s_barrier
	s_setprio 1
	v_mfma_f32_16x16x32_bf16 v[124:127], v[144:147], v[182:185], v[124:127]
	v_mfma_f32_16x16x32_bf16 v[120:123], v[158:161], v[182:185], v[120:123]
	v_mfma_f32_16x16x32_bf16 v[112:115], v[144:147], v[190:193], v[112:115]
	v_mfma_f32_16x16x32_bf16 v[104:107], v[158:161], v[190:193], v[104:107]
	v_mfma_f32_16x16x32_bf16 v[96:99], v[144:147], v[198:201], v[96:99]
	v_mfma_f32_16x16x32_bf16 v[88:91], v[158:161], v[198:201], v[88:91]
	v_mfma_f32_16x16x32_bf16 v[80:83], v[144:147], v[206:209], v[80:83]
	v_mfma_f32_16x16x32_bf16 v[72:75], v[158:161], v[206:209], v[72:75]
	v_mfma_f32_16x16x32_bf16 v[124:127], v[154:157], v[186:189], v[124:127]
	v_mfma_f32_16x16x32_bf16 v[120:123], v[162:165], v[186:189], v[120:123]
	v_mfma_f32_16x16x32_bf16 v[112:115], v[154:157], v[194:197], v[112:115]
	v_mfma_f32_16x16x32_bf16 v[104:107], v[162:165], v[194:197], v[104:107]
	v_mfma_f32_16x16x32_bf16 v[96:99], v[154:157], v[202:205], v[96:99]
	v_mfma_f32_16x16x32_bf16 v[88:91], v[162:165], v[202:205], v[88:91]
	v_mfma_f32_16x16x32_bf16 v[80:83], v[154:157], v[210:213], v[80:83]
	v_mfma_f32_16x16x32_bf16 v[72:75], v[162:165], v[210:213], v[72:75]
	s_setprio 0
	s_setprio 1
	v_mfma_f32_16x16x32_bf16 v[116:119], v[166:169], v[182:185], v[116:119]
	v_mfma_f32_16x16x32_bf16 v[108:111], v[174:177], v[182:185], v[108:111]
	v_mfma_f32_16x16x32_bf16 v[100:103], v[166:169], v[190:193], v[100:103]
	v_mfma_f32_16x16x32_bf16 v[92:95], v[174:177], v[190:193], v[92:95]
	v_mfma_f32_16x16x32_bf16 v[84:87], v[166:169], v[198:201], v[84:87]
	v_mfma_f32_16x16x32_bf16 v[76:79], v[174:177], v[198:201], v[76:79]
	v_mfma_f32_16x16x32_bf16 v[68:71], v[166:169], v[206:209], v[68:71]
	v_mfma_f32_16x16x32_bf16 v[64:67], v[174:177], v[206:209], v[64:67]
	v_mfma_f32_16x16x32_bf16 v[116:119], v[170:173], v[186:189], v[116:119]
	v_mfma_f32_16x16x32_bf16 v[108:111], v[178:181], v[186:189], v[108:111]
	s_setprio 2
	s_barrier
	v_mfma_f32_16x16x32_bf16 v[100:103], v[170:173], v[194:197], v[100:103]
	v_mfma_f32_16x16x32_bf16 v[92:95], v[178:181], v[194:197], v[92:95]
	v_mfma_f32_16x16x32_bf16 v[84:87], v[170:173], v[202:205], v[84:87]
	v_mfma_f32_16x16x32_bf16 v[76:79], v[178:181], v[202:205], v[76:79]
	v_mfma_f32_16x16x32_bf16 v[68:71], v[170:173], v[210:213], v[68:71]
	v_mfma_f32_16x16x32_bf16 v[64:67], v[178:181], v[210:213], v[64:67]
	s_setprio 0
	s_add_i32 s68, s56, s46
	v_lshl_add_u64 v[214:215], s[30:31], 0, v[130:131]
	s_mov_b32 m0, s68
	ds_read_b128 v[182:185], v151 offset:16384
	ds_read_b128 v[186:189], v151 offset:17408
	ds_read_b128 v[190:193], v151 offset:18432
	ds_read_b128 v[194:197], v151 offset:19456
	ds_read_b128 v[198:201], v151 offset:20480
	ds_read_b128 v[202:205], v151 offset:21504
	ds_read_b128 v[206:209], v151 offset:22528
	ds_read_b128 v[210:213], v151 offset:23552
	global_load_lds_dwordx4 v[214:215], off
	s_add_i32 m0, s68, 0x2000
	s_add_u32 s68, s30, 0x100000
	v_lshl_add_u64 v[216:217], s[30:31], 0, v[134:135]
	s_addc_u32 s69, s31, 0
	s_add_i32 s70, s57, s46
	global_load_lds_dwordx4 v[216:217], off
	v_lshl_add_u64 v[218:219], s[68:69], 0, v[130:131]
	s_mov_b32 m0, s70
	v_lshl_add_u64 v[220:221], s[36:37], 0, v[132:133]
	global_load_lds_dwordx4 v[218:219], off
	v_lshl_add_u64 v[218:219], s[68:69], 0, v[134:135]
	s_add_i32 m0, s70, 0x2000
	s_nop 0
	global_load_lds_dwordx4 v[218:219], off
	v_lshl_add_u64 v[218:219], s[36:37], 0, v[128:129]
	s_mov_b32 m0, s27
	s_nop 0
	global_load_lds_dwordx4 v[218:219], off
	s_mov_b32 m0, s47
	s_nop 0
	global_load_lds_dwordx4 v[220:221], off
	s_waitcnt vmcnt(8)
	s_waitcnt lgkmcnt(0)
	s_barrier
	s_setprio 1
	v_mfma_f32_16x16x32_bf16 v[60:63], v[144:147], v[182:185], v[60:63]
	v_mfma_f32_16x16x32_bf16 v[56:59], v[158:161], v[182:185], v[56:59]
	v_mfma_f32_16x16x32_bf16 v[48:51], v[144:147], v[190:193], v[48:51]
	v_mfma_f32_16x16x32_bf16 v[40:43], v[158:161], v[190:193], v[40:43]
	v_mfma_f32_16x16x32_bf16 v[32:35], v[144:147], v[198:201], v[32:35]
	v_mfma_f32_16x16x32_bf16 v[24:27], v[158:161], v[198:201], v[24:27]
	v_mfma_f32_16x16x32_bf16 v[16:19], v[144:147], v[206:209], v[16:19]
	v_mfma_f32_16x16x32_bf16 v[8:11], v[158:161], v[206:209], v[8:11]
	v_mfma_f32_16x16x32_bf16 v[60:63], v[154:157], v[186:189], v[60:63]
	v_mfma_f32_16x16x32_bf16 v[56:59], v[162:165], v[186:189], v[56:59]
	v_mfma_f32_16x16x32_bf16 v[48:51], v[154:157], v[194:197], v[48:51]
	v_mfma_f32_16x16x32_bf16 v[40:43], v[162:165], v[194:197], v[40:43]
	v_mfma_f32_16x16x32_bf16 v[32:35], v[154:157], v[202:205], v[32:35]
	v_mfma_f32_16x16x32_bf16 v[24:27], v[162:165], v[202:205], v[24:27]
	v_mfma_f32_16x16x32_bf16 v[16:19], v[154:157], v[210:213], v[16:19]
	v_mfma_f32_16x16x32_bf16 v[8:11], v[162:165], v[210:213], v[8:11]
	s_setprio 0
	s_setprio 1
	v_mfma_f32_16x16x32_bf16 v[52:55], v[166:169], v[182:185], v[52:55]
	v_mfma_f32_16x16x32_bf16 v[44:47], v[174:177], v[182:185], v[44:47]
	v_mfma_f32_16x16x32_bf16 v[36:39], v[166:169], v[190:193], v[36:39]
	v_mfma_f32_16x16x32_bf16 v[28:31], v[174:177], v[190:193], v[28:31]
	v_mfma_f32_16x16x32_bf16 v[20:23], v[166:169], v[198:201], v[20:23]
	v_mfma_f32_16x16x32_bf16 v[12:15], v[174:177], v[198:201], v[12:15]
	v_mfma_f32_16x16x32_bf16 v[4:7], v[166:169], v[206:209], v[4:7]
	v_mfma_f32_16x16x32_bf16 v[0:3], v[174:177], v[206:209], v[0:3]
	v_mfma_f32_16x16x32_bf16 v[52:55], v[170:173], v[186:189], v[52:55]
	v_mfma_f32_16x16x32_bf16 v[44:47], v[178:181], v[186:189], v[44:47]
	s_setprio 2
	s_barrier
	v_mfma_f32_16x16x32_bf16 v[36:39], v[170:173], v[194:197], v[36:39]
	v_mfma_f32_16x16x32_bf16 v[28:31], v[178:181], v[194:197], v[28:31]
	v_mfma_f32_16x16x32_bf16 v[20:23], v[170:173], v[202:205], v[20:23]
	v_mfma_f32_16x16x32_bf16 v[12:15], v[178:181], v[202:205], v[12:15]
	v_mfma_f32_16x16x32_bf16 v[4:7], v[170:173], v[210:213], v[4:7]
	v_mfma_f32_16x16x32_bf16 v[0:3], v[178:181], v[210:213], v[0:3]
	s_setprio 0
	s_add_i32 s68, 0, 0x18000
	v_add_u32_e32 v153, s68, v148
	s_add_i32 s69, 0, 0x1c000
	ds_read_b128 v[144:147], v153
	ds_read_b128 v[154:157], v153 offset:1024
	ds_read_b128 v[158:161], v153 offset:2048
	ds_read_b128 v[162:165], v153 offset:3072
	v_add_u32_e32 v153, s69, v148
	ds_read_b128 v[166:169], v153
	ds_read_b128 v[170:173], v153 offset:1024
	ds_read_b128 v[174:177], v153 offset:2048
	ds_read_b128 v[178:181], v153 offset:3072
	s_add_u32 s36, s36, 0x100000
	s_addc_u32 s37, s37, 0
	s_mov_b32 m0, s48
	v_lshl_add_u64 v[222:223], s[36:37], 0, v[128:129]
	ds_read_b128 v[182:185], v151 offset:32768
	ds_read_b128 v[186:189], v151 offset:33792
	ds_read_b128 v[190:193], v151 offset:34816
	ds_read_b128 v[194:197], v151 offset:35840
	ds_read_b128 v[198:201], v151 offset:36864
	ds_read_b128 v[202:205], v151 offset:37888
	ds_read_b128 v[206:209], v151 offset:38912
	ds_read_b128 v[210:213], v151 offset:39936
	global_load_lds_dwordx4 v[222:223], off
	v_lshl_add_u64 v[222:223], s[36:37], 0, v[132:133]
	s_mov_b32 m0, s49
	s_nop 0
	global_load_lds_dwordx4 v[222:223], off
	s_waitcnt vmcnt(8)
	s_waitcnt lgkmcnt(0)
	s_barrier
	s_setprio 1
	v_mfma_f32_16x16x32_bf16 v[124:127], v[144:147], v[182:185], v[124:127]
	v_mfma_f32_16x16x32_bf16 v[120:123], v[158:161], v[182:185], v[120:123]
	v_mfma_f32_16x16x32_bf16 v[112:115], v[144:147], v[190:193], v[112:115]
	v_mfma_f32_16x16x32_bf16 v[104:107], v[158:161], v[190:193], v[104:107]
	v_mfma_f32_16x16x32_bf16 v[96:99], v[144:147], v[198:201], v[96:99]
	v_mfma_f32_16x16x32_bf16 v[88:91], v[158:161], v[198:201], v[88:91]
	v_mfma_f32_16x16x32_bf16 v[80:83], v[144:147], v[206:209], v[80:83]
	v_mfma_f32_16x16x32_bf16 v[72:75], v[158:161], v[206:209], v[72:75]
	v_mfma_f32_16x16x32_bf16 v[124:127], v[154:157], v[186:189], v[124:127]
	v_mfma_f32_16x16x32_bf16 v[120:123], v[162:165], v[186:189], v[120:123]
	v_mfma_f32_16x16x32_bf16 v[112:115], v[154:157], v[194:197], v[112:115]
	v_mfma_f32_16x16x32_bf16 v[104:107], v[162:165], v[194:197], v[104:107]
	v_mfma_f32_16x16x32_bf16 v[96:99], v[154:157], v[202:205], v[96:99]
	v_mfma_f32_16x16x32_bf16 v[88:91], v[162:165], v[202:205], v[88:91]
	v_mfma_f32_16x16x32_bf16 v[80:83], v[154:157], v[210:213], v[80:83]
	v_mfma_f32_16x16x32_bf16 v[72:75], v[162:165], v[210:213], v[72:75]
	s_setprio 0
	s_setprio 1
	v_mfma_f32_16x16x32_bf16 v[116:119], v[166:169], v[182:185], v[116:119]
	v_mfma_f32_16x16x32_bf16 v[108:111], v[174:177], v[182:185], v[108:111]
	v_mfma_f32_16x16x32_bf16 v[100:103], v[166:169], v[190:193], v[100:103]
	v_mfma_f32_16x16x32_bf16 v[92:95], v[174:177], v[190:193], v[92:95]
	v_mfma_f32_16x16x32_bf16 v[84:87], v[166:169], v[198:201], v[84:87]
	v_mfma_f32_16x16x32_bf16 v[76:79], v[174:177], v[198:201], v[76:79]
	v_mfma_f32_16x16x32_bf16 v[68:71], v[166:169], v[206:209], v[68:71]
	v_mfma_f32_16x16x32_bf16 v[64:67], v[174:177], v[206:209], v[64:67]
	v_mfma_f32_16x16x32_bf16 v[116:119], v[170:173], v[186:189], v[116:119]
	v_mfma_f32_16x16x32_bf16 v[108:111], v[178:181], v[186:189], v[108:111]
	s_setprio 2
	s_barrier
	v_mfma_f32_16x16x32_bf16 v[100:103], v[170:173], v[194:197], v[100:103]
	v_mfma_f32_16x16x32_bf16 v[92:95], v[178:181], v[194:197], v[92:95]
	v_mfma_f32_16x16x32_bf16 v[84:87], v[170:173], v[202:205], v[84:87]
	v_mfma_f32_16x16x32_bf16 v[76:79], v[178:181], v[202:205], v[76:79]
	v_mfma_f32_16x16x32_bf16 v[68:71], v[170:173], v[210:213], v[68:71]
	v_mfma_f32_16x16x32_bf16 v[64:67], v[178:181], v[210:213], v[64:67]
	s_setprio 0
	s_add_i32 s36, s68, s46
	v_lshl_add_u64 v[214:215], v[214:215], 0, s[14:15]
	s_mov_b32 m0, s36
	ds_read_b128 v[182:185], v151 offset:49152
	ds_read_b128 v[186:189], v151 offset:50176
	ds_read_b128 v[190:193], v151 offset:51200
	ds_read_b128 v[194:197], v151 offset:52224
	ds_read_b128 v[198:201], v151 offset:53248
	ds_read_b128 v[202:205], v151 offset:54272
	ds_read_b128 v[206:209], v151 offset:55296
	ds_read_b128 v[210:213], v151 offset:56320
	global_load_lds_dwordx4 v[214:215], off
	s_add_i32 m0, s36, 0x2000
	s_add_u32 s30, s30, 0x100080
	v_lshl_add_u64 v[214:215], v[216:217], 0, s[14:15]
	s_addc_u32 s31, s31, 0
	s_add_i32 s36, s69, s46
	global_load_lds_dwordx4 v[214:215], off
	v_lshl_add_u64 v[214:215], s[30:31], 0, v[130:131]
	s_mov_b32 m0, s36
	s_nop 0
	global_load_lds_dwordx4 v[214:215], off
	v_lshl_add_u64 v[214:215], s[30:31], 0, v[134:135]
	s_add_i32 m0, s36, 0x2000
	s_nop 0
	global_load_lds_dwordx4 v[214:215], off
	v_lshl_add_u64 v[214:215], v[218:219], 0, s[14:15]
	s_mov_b32 m0, s53
	s_nop 0
	global_load_lds_dwordx4 v[214:215], off
	v_lshl_add_u64 v[214:215], v[220:221], 0, s[14:15]
	s_mov_b32 m0, s54
	s_nop 0
	global_load_lds_dwordx4 v[214:215], off
	s_waitcnt vmcnt(8)
	s_waitcnt lgkmcnt(0)
	s_barrier
	s_setprio 1
	v_mfma_f32_16x16x32_bf16 v[60:63], v[144:147], v[182:185], v[60:63]
	v_mfma_f32_16x16x32_bf16 v[56:59], v[158:161], v[182:185], v[56:59]
	v_mfma_f32_16x16x32_bf16 v[48:51], v[144:147], v[190:193], v[48:51]
	v_mfma_f32_16x16x32_bf16 v[40:43], v[158:161], v[190:193], v[40:43]
	v_mfma_f32_16x16x32_bf16 v[32:35], v[144:147], v[198:201], v[32:35]
	v_mfma_f32_16x16x32_bf16 v[24:27], v[158:161], v[198:201], v[24:27]
	v_mfma_f32_16x16x32_bf16 v[16:19], v[144:147], v[206:209], v[16:19]
	v_mfma_f32_16x16x32_bf16 v[8:11], v[158:161], v[206:209], v[8:11]
	v_mfma_f32_16x16x32_bf16 v[60:63], v[154:157], v[186:189], v[60:63]
	v_mfma_f32_16x16x32_bf16 v[56:59], v[162:165], v[186:189], v[56:59]
	v_mfma_f32_16x16x32_bf16 v[48:51], v[154:157], v[194:197], v[48:51]
	v_mfma_f32_16x16x32_bf16 v[40:43], v[162:165], v[194:197], v[40:43]
	v_mfma_f32_16x16x32_bf16 v[32:35], v[154:157], v[202:205], v[32:35]
	v_mfma_f32_16x16x32_bf16 v[24:27], v[162:165], v[202:205], v[24:27]
	v_mfma_f32_16x16x32_bf16 v[16:19], v[154:157], v[210:213], v[16:19]
	v_mfma_f32_16x16x32_bf16 v[8:11], v[162:165], v[210:213], v[8:11]
	s_setprio 0
	s_setprio 1
	v_mfma_f32_16x16x32_bf16 v[52:55], v[166:169], v[182:185], v[52:55]
	v_mfma_f32_16x16x32_bf16 v[44:47], v[174:177], v[182:185], v[44:47]
	v_mfma_f32_16x16x32_bf16 v[36:39], v[166:169], v[190:193], v[36:39]
	v_mfma_f32_16x16x32_bf16 v[28:31], v[174:177], v[190:193], v[28:31]
	v_mfma_f32_16x16x32_bf16 v[20:23], v[166:169], v[198:201], v[20:23]
	v_mfma_f32_16x16x32_bf16 v[12:15], v[174:177], v[198:201], v[12:15]
	v_mfma_f32_16x16x32_bf16 v[4:7], v[166:169], v[206:209], v[4:7]
	v_mfma_f32_16x16x32_bf16 v[0:3], v[174:177], v[206:209], v[0:3]
	v_mfma_f32_16x16x32_bf16 v[52:55], v[170:173], v[186:189], v[52:55]
	v_mfma_f32_16x16x32_bf16 v[44:47], v[178:181], v[186:189], v[44:47]
	s_setprio 2
	s_barrier
	v_mfma_f32_16x16x32_bf16 v[36:39], v[170:173], v[194:197], v[36:39]
	v_mfma_f32_16x16x32_bf16 v[28:31], v[178:181], v[194:197], v[28:31]
	v_mfma_f32_16x16x32_bf16 v[20:23], v[170:173], v[202:205], v[20:23]
	v_mfma_f32_16x16x32_bf16 v[12:15], v[178:181], v[202:205], v[12:15]
	v_mfma_f32_16x16x32_bf16 v[4:7], v[170:173], v[210:213], v[4:7]
	v_mfma_f32_16x16x32_bf16 v[0:3], v[178:181], v[210:213], v[0:3]
	s_setprio 0
	s_add_i32 s67, s67, 2
	s_add_u32 s28, s28, 0x100
	s_addc_u32 s29, s29, 0
	s_add_u32 s61, s61, 0x100
	s_addc_u32 s62, s62, 0
	s_cmp_gt_u32 s67, 61
	s_cbranch_scc0 .LBB0_229

.LBB0_633:
	v_add_u32_e32 v160, s68, v164
	v_add_u32_e32 v178, s69, v164
	s_add_u32 s48, s38, s46
	ds_read_b128 v[148:151], v160
	ds_read_b128 v[152:155], v160 offset:1024
	ds_read_b128 v[156:159], v160 offset:2048
	ds_read_b128 v[160:163], v160 offset:3072
	ds_read_b128 v[166:169], v178
	ds_read_b128 v[170:173], v178 offset:1024
	ds_read_b128 v[174:177], v178 offset:2048
	ds_read_b128 v[178:181], v178 offset:3072
	s_addc_u32 s49, s39, s47
	s_add_u32 s48, s48, 0x100
	s_addc_u32 s49, s49, 0
	s_add_u32 s67, s74, s46
	s_addc_u32 s77, s75, s47
	s_cmpk_eq_i32 s46, 0xf00
	s_cselect_b32 s51, s29, s49
	s_cselect_b32 s50, s71, s48
	s_cselect_b32 s49, s72, s77
	s_cselect_b32 s48, s73, s67
	v_lshl_add_u64 v[214:215], v[144:145], 0, s[46:47]
	s_add_i32 m0, s54, 0xc000
	ds_read_b128 v[182:185], v165
	ds_read_b128 v[186:189], v165 offset:1024
	ds_read_b128 v[190:193], v165 offset:2048
	ds_read_b128 v[194:197], v165 offset:3072
	ds_read_b128 v[198:201], v165 offset:4096
	ds_read_b128 v[202:205], v165 offset:5120
	ds_read_b128 v[206:209], v165 offset:6144
	ds_read_b128 v[210:213], v165 offset:7168
	global_load_lds_dwordx4 v[214:215], off
	v_lshl_add_u64 v[214:215], v[146:147], 0, s[46:47]
	s_add_i32 m0, s54, 0xe000
	s_nop 0
	global_load_lds_dwordx4 v[214:215], off
	s_waitcnt vmcnt(8)
	s_waitcnt lgkmcnt(0)
	s_barrier
	s_setprio 1
	v_mfma_i32_16x16x64_i8 v[124:127], v[148:151], v[182:185], v[124:127]
	v_mfma_i32_16x16x64_i8 v[120:123], v[156:159], v[182:185], v[120:123]
	v_mfma_i32_16x16x64_i8 v[108:111], v[148:151], v[190:193], v[108:111]
	v_mfma_i32_16x16x64_i8 v[104:107], v[156:159], v[190:193], v[104:107]
	v_mfma_i32_16x16x64_i8 v[92:95], v[148:151], v[198:201], v[92:95]
	v_mfma_i32_16x16x64_i8 v[88:91], v[156:159], v[198:201], v[88:91]
	v_mfma_i32_16x16x64_i8 v[76:79], v[148:151], v[206:209], v[76:79]
	v_mfma_i32_16x16x64_i8 v[72:75], v[156:159], v[206:209], v[72:75]
	v_mfma_i32_16x16x64_i8 v[124:127], v[152:155], v[186:189], v[124:127]
	v_mfma_i32_16x16x64_i8 v[120:123], v[160:163], v[186:189], v[120:123]
	v_mfma_i32_16x16x64_i8 v[108:111], v[152:155], v[194:197], v[108:111]
	v_mfma_i32_16x16x64_i8 v[104:107], v[160:163], v[194:197], v[104:107]
	v_mfma_i32_16x16x64_i8 v[92:95], v[152:155], v[202:205], v[92:95]
	v_mfma_i32_16x16x64_i8 v[88:91], v[160:163], v[202:205], v[88:91]
	v_mfma_i32_16x16x64_i8 v[76:79], v[152:155], v[210:213], v[76:79]
	v_mfma_i32_16x16x64_i8 v[72:75], v[160:163], v[210:213], v[72:75]
	s_setprio 0
	s_setprio 1
	v_mfma_i32_16x16x64_i8 v[116:119], v[166:169], v[182:185], v[116:119]
	v_mfma_i32_16x16x64_i8 v[112:115], v[174:177], v[182:185], v[112:115]
	v_mfma_i32_16x16x64_i8 v[100:103], v[166:169], v[190:193], v[100:103]
	v_mfma_i32_16x16x64_i8 v[96:99], v[174:177], v[190:193], v[96:99]
	v_mfma_i32_16x16x64_i8 v[84:87], v[166:169], v[198:201], v[84:87]
	v_mfma_i32_16x16x64_i8 v[80:83], v[174:177], v[198:201], v[80:83]
	v_mfma_i32_16x16x64_i8 v[68:71], v[166:169], v[206:209], v[68:71]
	v_mfma_i32_16x16x64_i8 v[64:67], v[174:177], v[206:209], v[64:67]
	v_mfma_i32_16x16x64_i8 v[116:119], v[170:173], v[186:189], v[116:119]
	v_mfma_i32_16x16x64_i8 v[112:115], v[178:181], v[186:189], v[112:115]
	v_mfma_i32_16x16x64_i8 v[100:103], v[170:173], v[194:197], v[100:103]
	s_setprio 2
	s_barrier
	v_mfma_i32_16x16x64_i8 v[96:99], v[178:181], v[194:197], v[96:99]
	v_mfma_i32_16x16x64_i8 v[84:87], v[170:173], v[202:205], v[84:87]
	v_mfma_i32_16x16x64_i8 v[80:83], v[178:181], v[202:205], v[80:83]
	v_mfma_i32_16x16x64_i8 v[68:71], v[170:173], v[210:213], v[68:71]
	v_mfma_i32_16x16x64_i8 v[64:67], v[178:181], v[210:213], v[64:67]
	s_setprio 0
	s_add_i32 s67, s68, s45
	v_lshl_add_u64 v[214:215], s[48:49], 0, v[132:133]
	s_mov_b32 m0, s67
	ds_read_b128 v[182:185], v165 offset:16384
	ds_read_b128 v[186:189], v165 offset:17408
	ds_read_b128 v[190:193], v165 offset:18432
	ds_read_b128 v[194:197], v165 offset:19456
	ds_read_b128 v[198:201], v165 offset:20480
	ds_read_b128 v[202:205], v165 offset:21504
	ds_read_b128 v[206:209], v165 offset:22528
	ds_read_b128 v[210:213], v165 offset:23552
	global_load_lds_dwordx4 v[214:215], off
	s_add_i32 m0, s67, 0x2000
	s_add_u32 s78, s48, 0x80000
	v_lshl_add_u64 v[216:217], s[48:49], 0, v[128:129]
	s_addc_u32 s79, s49, 0
	s_add_i32 s67, s69, s45
	global_load_lds_dwordx4 v[216:217], off
	v_lshl_add_u64 v[218:219], s[78:79], 0, v[132:133]
	s_mov_b32 m0, s67
	v_lshl_add_u64 v[220:221], s[50:51], 0, v[130:131]
	global_load_lds_dwordx4 v[218:219], off
	v_lshl_add_u64 v[218:219], s[78:79], 0, v[128:129]
	s_add_i32 m0, s67, 0x2000
	s_nop 0
	global_load_lds_dwordx4 v[218:219], off
	v_lshl_add_u64 v[218:219], s[50:51], 0, v[134:135]
	s_mov_b32 m0, s54
	s_nop 0
	global_load_lds_dwordx4 v[218:219], off
	s_mov_b32 m0, s55
	s_nop 0
	global_load_lds_dwordx4 v[220:221], off
	s_waitcnt vmcnt(8)
	s_waitcnt lgkmcnt(0)
	s_barrier
	s_setprio 1
	v_mfma_i32_16x16x64_i8 v[60:63], v[148:151], v[182:185], v[60:63]
	v_mfma_i32_16x16x64_i8 v[56:59], v[156:159], v[182:185], v[56:59]
	v_mfma_i32_16x16x64_i8 v[44:47], v[148:151], v[190:193], v[44:47]
	v_mfma_i32_16x16x64_i8 v[40:43], v[156:159], v[190:193], v[40:43]
	v_mfma_i32_16x16x64_i8 v[28:31], v[148:151], v[198:201], v[28:31]
	v_mfma_i32_16x16x64_i8 v[24:27], v[156:159], v[198:201], v[24:27]
	v_mfma_i32_16x16x64_i8 v[12:15], v[148:151], v[206:209], v[12:15]
	v_mfma_i32_16x16x64_i8 v[8:11], v[156:159], v[206:209], v[8:11]
	v_mfma_i32_16x16x64_i8 v[60:63], v[152:155], v[186:189], v[60:63]
	v_mfma_i32_16x16x64_i8 v[56:59], v[160:163], v[186:189], v[56:59]
	v_mfma_i32_16x16x64_i8 v[44:47], v[152:155], v[194:197], v[44:47]
	v_mfma_i32_16x16x64_i8 v[40:43], v[160:163], v[194:197], v[40:43]
	v_mfma_i32_16x16x64_i8 v[28:31], v[152:155], v[202:205], v[28:31]
	v_mfma_i32_16x16x64_i8 v[24:27], v[160:163], v[202:205], v[24:27]
	v_mfma_i32_16x16x64_i8 v[12:15], v[152:155], v[210:213], v[12:15]
	v_mfma_i32_16x16x64_i8 v[8:11], v[160:163], v[210:213], v[8:11]
	s_setprio 0
	s_setprio 1
	v_mfma_i32_16x16x64_i8 v[52:55], v[166:169], v[182:185], v[52:55]
	v_mfma_i32_16x16x64_i8 v[48:51], v[174:177], v[182:185], v[48:51]
	v_mfma_i32_16x16x64_i8 v[36:39], v[166:169], v[190:193], v[36:39]
	v_mfma_i32_16x16x64_i8 v[32:35], v[174:177], v[190:193], v[32:35]
	v_mfma_i32_16x16x64_i8 v[20:23], v[166:169], v[198:201], v[20:23]
	v_mfma_i32_16x16x64_i8 v[16:19], v[174:177], v[198:201], v[16:19]
	v_mfma_i32_16x16x64_i8 v[4:7], v[166:169], v[206:209], v[4:7]
	v_mfma_i32_16x16x64_i8 v[0:3], v[174:177], v[206:209], v[0:3]
	v_mfma_i32_16x16x64_i8 v[52:55], v[170:173], v[186:189], v[52:55]
	v_mfma_i32_16x16x64_i8 v[48:51], v[178:181], v[186:189], v[48:51]
	v_mfma_i32_16x16x64_i8 v[36:39], v[170:173], v[194:197], v[36:39]
	s_setprio 2
	s_barrier
	v_mfma_i32_16x16x64_i8 v[32:35], v[178:181], v[194:197], v[32:35]
	v_mfma_i32_16x16x64_i8 v[20:23], v[170:173], v[202:205], v[20:23]
	v_mfma_i32_16x16x64_i8 v[16:19], v[178:181], v[202:205], v[16:19]
	v_mfma_i32_16x16x64_i8 v[4:7], v[170:173], v[210:213], v[4:7]
	v_mfma_i32_16x16x64_i8 v[0:3], v[178:181], v[210:213], v[0:3]
	s_setprio 0
	s_add_i32 s67, 0, 0x18000
	s_add_i32 s77, 0, 0x1c000
	v_add_u32_e32 v160, s67, v164
	v_add_u32_e32 v178, s77, v164
	ds_read_b128 v[148:151], v160
	ds_read_b128 v[152:155], v160 offset:1024
	ds_read_b128 v[156:159], v160 offset:2048
	ds_read_b128 v[160:163], v160 offset:3072
	ds_read_b128 v[166:169], v178
	ds_read_b128 v[170:173], v178 offset:1024
	ds_read_b128 v[174:177], v178 offset:2048
	ds_read_b128 v[178:181], v178 offset:3072
	s_add_u32 s50, s50, 0x80000
	s_addc_u32 s51, s51, 0
	s_mov_b32 m0, s56
	v_lshl_add_u64 v[222:223], s[50:51], 0, v[134:135]
	ds_read_b128 v[182:185], v165 offset:32768
	ds_read_b128 v[186:189], v165 offset:33792
	ds_read_b128 v[190:193], v165 offset:34816
	ds_read_b128 v[194:197], v165 offset:35840
	ds_read_b128 v[198:201], v165 offset:36864
	ds_read_b128 v[202:205], v165 offset:37888
	ds_read_b128 v[206:209], v165 offset:38912
	ds_read_b128 v[210:213], v165 offset:39936
	global_load_lds_dwordx4 v[222:223], off
	v_lshl_add_u64 v[222:223], s[50:51], 0, v[130:131]
	s_mov_b32 m0, s57
	s_nop 0
	global_load_lds_dwordx4 v[222:223], off
	s_waitcnt vmcnt(8)
	s_waitcnt lgkmcnt(0)
	s_barrier
	s_setprio 1
	v_mfma_i32_16x16x64_i8 v[124:127], v[148:151], v[182:185], v[124:127]
	v_mfma_i32_16x16x64_i8 v[120:123], v[156:159], v[182:185], v[120:123]
	v_mfma_i32_16x16x64_i8 v[108:111], v[148:151], v[190:193], v[108:111]
	v_mfma_i32_16x16x64_i8 v[104:107], v[156:159], v[190:193], v[104:107]
	v_mfma_i32_16x16x64_i8 v[92:95], v[148:151], v[198:201], v[92:95]
	v_mfma_i32_16x16x64_i8 v[88:91], v[156:159], v[198:201], v[88:91]
	v_mfma_i32_16x16x64_i8 v[76:79], v[148:151], v[206:209], v[76:79]
	v_mfma_i32_16x16x64_i8 v[72:75], v[156:159], v[206:209], v[72:75]
	v_mfma_i32_16x16x64_i8 v[124:127], v[152:155], v[186:189], v[124:127]
	v_mfma_i32_16x16x64_i8 v[120:123], v[160:163], v[186:189], v[120:123]
	v_mfma_i32_16x16x64_i8 v[108:111], v[152:155], v[194:197], v[108:111]
	v_mfma_i32_16x16x64_i8 v[104:107], v[160:163], v[194:197], v[104:107]
	v_mfma_i32_16x16x64_i8 v[92:95], v[152:155], v[202:205], v[92:95]
	v_mfma_i32_16x16x64_i8 v[88:91], v[160:163], v[202:205], v[88:91]
	v_mfma_i32_16x16x64_i8 v[76:79], v[152:155], v[210:213], v[76:79]
	v_mfma_i32_16x16x64_i8 v[72:75], v[160:163], v[210:213], v[72:75]
	s_setprio 0
	s_setprio 1
	v_mfma_i32_16x16x64_i8 v[116:119], v[166:169], v[182:185], v[116:119]
	v_mfma_i32_16x16x64_i8 v[112:115], v[174:177], v[182:185], v[112:115]
	v_mfma_i32_16x16x64_i8 v[100:103], v[166:169], v[190:193], v[100:103]
	v_mfma_i32_16x16x64_i8 v[96:99], v[174:177], v[190:193], v[96:99]
	v_mfma_i32_16x16x64_i8 v[84:87], v[166:169], v[198:201], v[84:87]
	v_mfma_i32_16x16x64_i8 v[80:83], v[174:177], v[198:201], v[80:83]
	v_mfma_i32_16x16x64_i8 v[68:71], v[166:169], v[206:209], v[68:71]
	v_mfma_i32_16x16x64_i8 v[64:67], v[174:177], v[206:209], v[64:67]
	v_mfma_i32_16x16x64_i8 v[116:119], v[170:173], v[186:189], v[116:119]
	v_mfma_i32_16x16x64_i8 v[112:115], v[178:181], v[186:189], v[112:115]
	v_mfma_i32_16x16x64_i8 v[100:103], v[170:173], v[194:197], v[100:103]
	s_setprio 2
	s_barrier
	v_mfma_i32_16x16x64_i8 v[96:99], v[178:181], v[194:197], v[96:99]
	v_mfma_i32_16x16x64_i8 v[84:87], v[170:173], v[202:205], v[84:87]
	v_mfma_i32_16x16x64_i8 v[80:83], v[178:181], v[202:205], v[80:83]
	v_mfma_i32_16x16x64_i8 v[68:71], v[170:173], v[210:213], v[68:71]
	v_mfma_i32_16x16x64_i8 v[64:67], v[178:181], v[210:213], v[64:67]
	s_setprio 0
	s_add_i32 s50, s67, s45
	v_lshl_add_u64 v[214:215], v[214:215], 0, s[18:19]
	s_mov_b32 m0, s50
	ds_read_b128 v[182:185], v165 offset:49152
	ds_read_b128 v[186:189], v165 offset:50176
	ds_read_b128 v[190:193], v165 offset:51200
	ds_read_b128 v[194:197], v165 offset:52224
	ds_read_b128 v[198:201], v165 offset:53248
	ds_read_b128 v[202:205], v165 offset:54272
	ds_read_b128 v[206:209], v165 offset:55296
	ds_read_b128 v[210:213], v165 offset:56320
	global_load_lds_dwordx4 v[214:215], off
	s_add_i32 m0, s50, 0x2000
	s_add_u32 s48, s48, 0x80080
	v_lshl_add_u64 v[214:215], v[216:217], 0, s[18:19]
	s_addc_u32 s49, s49, 0
	s_add_i32 s50, s77, s45
	global_load_lds_dwordx4 v[214:215], off
	v_lshl_add_u64 v[214:215], s[48:49], 0, v[132:133]
	s_mov_b32 m0, s50
	s_nop 0
	global_load_lds_dwordx4 v[214:215], off
	v_lshl_add_u64 v[214:215], s[48:49], 0, v[128:129]
	s_add_i32 m0, s50, 0x2000
	s_nop 0
	global_load_lds_dwordx4 v[214:215], off
	v_lshl_add_u64 v[214:215], v[218:219], 0, s[18:19]
	s_mov_b32 m0, s60
	s_nop 0
	global_load_lds_dwordx4 v[214:215], off
	v_lshl_add_u64 v[214:215], v[220:221], 0, s[18:19]
	s_mov_b32 m0, s61
	s_nop 0
	global_load_lds_dwordx4 v[214:215], off
	s_waitcnt vmcnt(8)
	s_waitcnt lgkmcnt(0)
	s_barrier
	s_setprio 1
	v_mfma_i32_16x16x64_i8 v[60:63], v[148:151], v[182:185], v[60:63]
	v_mfma_i32_16x16x64_i8 v[56:59], v[156:159], v[182:185], v[56:59]
	v_mfma_i32_16x16x64_i8 v[44:47], v[148:151], v[190:193], v[44:47]
	v_mfma_i32_16x16x64_i8 v[40:43], v[156:159], v[190:193], v[40:43]
	v_mfma_i32_16x16x64_i8 v[28:31], v[148:151], v[198:201], v[28:31]
	v_mfma_i32_16x16x64_i8 v[24:27], v[156:159], v[198:201], v[24:27]
	v_mfma_i32_16x16x64_i8 v[12:15], v[148:151], v[206:209], v[12:15]
	v_mfma_i32_16x16x64_i8 v[8:11], v[156:159], v[206:209], v[8:11]
	v_mfma_i32_16x16x64_i8 v[60:63], v[152:155], v[186:189], v[60:63]
	v_mfma_i32_16x16x64_i8 v[56:59], v[160:163], v[186:189], v[56:59]
	v_mfma_i32_16x16x64_i8 v[44:47], v[152:155], v[194:197], v[44:47]
	v_mfma_i32_16x16x64_i8 v[40:43], v[160:163], v[194:197], v[40:43]
	v_mfma_i32_16x16x64_i8 v[28:31], v[152:155], v[202:205], v[28:31]
	v_mfma_i32_16x16x64_i8 v[24:27], v[160:163], v[202:205], v[24:27]
	v_mfma_i32_16x16x64_i8 v[12:15], v[152:155], v[210:213], v[12:15]
	v_mfma_i32_16x16x64_i8 v[8:11], v[160:163], v[210:213], v[8:11]
	s_setprio 0
	s_setprio 1
	v_mfma_i32_16x16x64_i8 v[52:55], v[166:169], v[182:185], v[52:55]
	v_mfma_i32_16x16x64_i8 v[48:51], v[174:177], v[182:185], v[48:51]
	v_mfma_i32_16x16x64_i8 v[36:39], v[166:169], v[190:193], v[36:39]
	v_mfma_i32_16x16x64_i8 v[32:35], v[174:177], v[190:193], v[32:35]
	v_mfma_i32_16x16x64_i8 v[20:23], v[166:169], v[198:201], v[20:23]
	v_mfma_i32_16x16x64_i8 v[16:19], v[174:177], v[198:201], v[16:19]
	v_mfma_i32_16x16x64_i8 v[4:7], v[166:169], v[206:209], v[4:7]
	v_mfma_i32_16x16x64_i8 v[0:3], v[174:177], v[206:209], v[0:3]
	v_mfma_i32_16x16x64_i8 v[52:55], v[170:173], v[186:189], v[52:55]
	v_mfma_i32_16x16x64_i8 v[48:51], v[178:181], v[186:189], v[48:51]
	v_mfma_i32_16x16x64_i8 v[36:39], v[170:173], v[194:197], v[36:39]
	s_setprio 2
	s_barrier
	v_mfma_i32_16x16x64_i8 v[32:35], v[178:181], v[194:197], v[32:35]
	v_mfma_i32_16x16x64_i8 v[20:23], v[170:173], v[202:205], v[20:23]
	v_mfma_i32_16x16x64_i8 v[16:19], v[178:181], v[202:205], v[16:19]
	v_mfma_i32_16x16x64_i8 v[4:7], v[170:173], v[210:213], v[4:7]
	v_mfma_i32_16x16x64_i8 v[0:3], v[178:181], v[210:213], v[0:3]
	s_setprio 0
	s_add_i32 s76, s76, 2
	s_add_u32 s46, s46, 0x100
	s_addc_u32 s47, s47, 0
	s_cmp_gt_u32 s76, 29
	s_cbranch_scc1 .LBB0_636

.LBB0_771:
	ds_read_b128 v[144:147], v153
	ds_read_b128 v[148:151], v153 offset:1024
	ds_read_b128 v[156:159], v153 offset:2048
	ds_read_b128 v[160:163], v153 offset:3072
	ds_read_b128 v[164:167], v154
	ds_read_b128 v[168:171], v154 offset:1024
	ds_read_b128 v[172:175], v154 offset:2048
	ds_read_b128 v[176:179], v154 offset:3072
	s_add_u32 s56, s54, 0xfff80080
	s_addc_u32 s57, s55, -1
	s_cmp_eq_u32 s79, 28
	s_cselect_b32 s59, s47, s57
	s_cselect_b32 s58, s75, s56
	s_cselect_b32 s57, s39, s78
	s_cselect_b32 s56, s76, s77
	v_lshl_add_u64 v[212:213], s[54:55], 0, v[136:137]
	s_add_i32 m0, s37, 0xc000
	ds_read_b128 v[180:183], v155
	ds_read_b128 v[184:187], v155 offset:1024
	ds_read_b128 v[188:191], v155 offset:2048
	ds_read_b128 v[192:195], v155 offset:3072
	ds_read_b128 v[196:199], v155 offset:4096
	ds_read_b128 v[200:203], v155 offset:5120
	ds_read_b128 v[204:207], v155 offset:6144
	ds_read_b128 v[208:211], v155 offset:7168
	global_load_lds_dwordx4 v[212:213], off
	v_lshl_add_u64 v[212:213], s[54:55], 0, v[138:139]
	s_add_i32 m0, s37, 0xe000
	s_nop 0
	global_load_lds_dwordx4 v[212:213], off
	s_waitcnt vmcnt(8)
	s_waitcnt lgkmcnt(0)
	s_barrier
	s_setprio 1
	v_mfma_i32_16x16x64_i8 v[124:127], v[144:147], v[180:183], v[124:127]
	v_mfma_i32_16x16x64_i8 v[120:123], v[156:159], v[180:183], v[120:123]
	v_mfma_i32_16x16x64_i8 v[108:111], v[144:147], v[188:191], v[108:111]
	v_mfma_i32_16x16x64_i8 v[104:107], v[156:159], v[188:191], v[104:107]
	v_mfma_i32_16x16x64_i8 v[92:95], v[144:147], v[196:199], v[92:95]
	v_mfma_i32_16x16x64_i8 v[88:91], v[156:159], v[196:199], v[88:91]
	v_mfma_i32_16x16x64_i8 v[76:79], v[144:147], v[204:207], v[76:79]
	v_mfma_i32_16x16x64_i8 v[72:75], v[156:159], v[204:207], v[72:75]
	v_mfma_i32_16x16x64_i8 v[124:127], v[148:151], v[184:187], v[124:127]
	v_mfma_i32_16x16x64_i8 v[120:123], v[160:163], v[184:187], v[120:123]
	v_mfma_i32_16x16x64_i8 v[108:111], v[148:151], v[192:195], v[108:111]
	v_mfma_i32_16x16x64_i8 v[104:107], v[160:163], v[192:195], v[104:107]
	v_mfma_i32_16x16x64_i8 v[92:95], v[148:151], v[200:203], v[92:95]
	v_mfma_i32_16x16x64_i8 v[88:91], v[160:163], v[200:203], v[88:91]
	v_mfma_i32_16x16x64_i8 v[76:79], v[148:151], v[208:211], v[76:79]
	v_mfma_i32_16x16x64_i8 v[72:75], v[160:163], v[208:211], v[72:75]
	s_setprio 0
	s_setprio 1
	v_mfma_i32_16x16x64_i8 v[116:119], v[164:167], v[180:183], v[116:119]
	v_mfma_i32_16x16x64_i8 v[112:115], v[172:175], v[180:183], v[112:115]
	v_mfma_i32_16x16x64_i8 v[100:103], v[164:167], v[188:191], v[100:103]
	v_mfma_i32_16x16x64_i8 v[96:99], v[172:175], v[188:191], v[96:99]
	v_mfma_i32_16x16x64_i8 v[84:87], v[164:167], v[196:199], v[84:87]
	v_mfma_i32_16x16x64_i8 v[80:83], v[172:175], v[196:199], v[80:83]
	v_mfma_i32_16x16x64_i8 v[68:71], v[164:167], v[204:207], v[68:71]
	v_mfma_i32_16x16x64_i8 v[64:67], v[172:175], v[204:207], v[64:67]
	v_mfma_i32_16x16x64_i8 v[116:119], v[168:171], v[184:187], v[116:119]
	v_mfma_i32_16x16x64_i8 v[112:115], v[176:179], v[184:187], v[112:115]
	v_mfma_i32_16x16x64_i8 v[100:103], v[168:171], v[192:195], v[100:103]
	s_setprio 2
	s_barrier
	v_mfma_i32_16x16x64_i8 v[96:99], v[176:179], v[192:195], v[96:99]
	v_mfma_i32_16x16x64_i8 v[84:87], v[168:171], v[200:203], v[84:87]
	v_mfma_i32_16x16x64_i8 v[80:83], v[176:179], v[200:203], v[80:83]
	v_mfma_i32_16x16x64_i8 v[68:71], v[168:171], v[208:211], v[68:71]
	v_mfma_i32_16x16x64_i8 v[64:67], v[176:179], v[208:211], v[64:67]
	s_setprio 0
	s_add_i32 s80, s72, s34
	v_lshl_add_u64 v[212:213], s[56:57], 0, v[132:133]
	s_mov_b32 m0, s80
	ds_read_b128 v[180:183], v155 offset:16384
	ds_read_b128 v[184:187], v155 offset:17408
	ds_read_b128 v[188:191], v155 offset:18432
	ds_read_b128 v[192:195], v155 offset:19456
	ds_read_b128 v[196:199], v155 offset:20480
	ds_read_b128 v[200:203], v155 offset:21504
	ds_read_b128 v[204:207], v155 offset:22528
	ds_read_b128 v[208:211], v155 offset:23552
	global_load_lds_dwordx4 v[212:213], off
	s_add_i32 m0, s80, 0x2000
	s_add_u32 s80, s56, 0x80000
	v_lshl_add_u64 v[214:215], s[56:57], 0, v[128:129]
	s_addc_u32 s81, s57, 0
	s_add_i32 s82, s73, s34
	global_load_lds_dwordx4 v[214:215], off
	v_lshl_add_u64 v[216:217], s[80:81], 0, v[132:133]
	s_mov_b32 m0, s82
	v_lshl_add_u64 v[218:219], s[58:59], 0, v[130:131]
	global_load_lds_dwordx4 v[216:217], off
	v_lshl_add_u64 v[216:217], s[80:81], 0, v[128:129]
	s_add_i32 m0, s82, 0x2000
	s_nop 0
	global_load_lds_dwordx4 v[216:217], off
	v_lshl_add_u64 v[216:217], s[58:59], 0, v[134:135]
	s_mov_b32 m0, s37
	s_nop 0
	global_load_lds_dwordx4 v[216:217], off
	s_mov_b32 m0, s45
	s_nop 0
	global_load_lds_dwordx4 v[218:219], off
	s_waitcnt vmcnt(8)
	s_waitcnt lgkmcnt(0)
	s_barrier
	s_setprio 1
	v_mfma_i32_16x16x64_i8 v[60:63], v[144:147], v[180:183], v[60:63]
	v_mfma_i32_16x16x64_i8 v[56:59], v[156:159], v[180:183], v[56:59]
	v_mfma_i32_16x16x64_i8 v[44:47], v[144:147], v[188:191], v[44:47]
	v_mfma_i32_16x16x64_i8 v[40:43], v[156:159], v[188:191], v[40:43]
	v_mfma_i32_16x16x64_i8 v[28:31], v[144:147], v[196:199], v[28:31]
	v_mfma_i32_16x16x64_i8 v[24:27], v[156:159], v[196:199], v[24:27]
	v_mfma_i32_16x16x64_i8 v[12:15], v[144:147], v[204:207], v[12:15]
	v_mfma_i32_16x16x64_i8 v[8:11], v[156:159], v[204:207], v[8:11]
	v_mfma_i32_16x16x64_i8 v[60:63], v[148:151], v[184:187], v[60:63]
	v_mfma_i32_16x16x64_i8 v[56:59], v[160:163], v[184:187], v[56:59]
	v_mfma_i32_16x16x64_i8 v[44:47], v[148:151], v[192:195], v[44:47]
	v_mfma_i32_16x16x64_i8 v[40:43], v[160:163], v[192:195], v[40:43]
	v_mfma_i32_16x16x64_i8 v[28:31], v[148:151], v[200:203], v[28:31]
	v_mfma_i32_16x16x64_i8 v[24:27], v[160:163], v[200:203], v[24:27]
	v_mfma_i32_16x16x64_i8 v[12:15], v[148:151], v[208:211], v[12:15]
	v_mfma_i32_16x16x64_i8 v[8:11], v[160:163], v[208:211], v[8:11]
	s_setprio 0
	s_setprio 1
	v_mfma_i32_16x16x64_i8 v[52:55], v[164:167], v[180:183], v[52:55]
	v_mfma_i32_16x16x64_i8 v[48:51], v[172:175], v[180:183], v[48:51]
	v_mfma_i32_16x16x64_i8 v[36:39], v[164:167], v[188:191], v[36:39]
	v_mfma_i32_16x16x64_i8 v[32:35], v[172:175], v[188:191], v[32:35]
	v_mfma_i32_16x16x64_i8 v[20:23], v[164:167], v[196:199], v[20:23]
	v_mfma_i32_16x16x64_i8 v[16:19], v[172:175], v[196:199], v[16:19]
	v_mfma_i32_16x16x64_i8 v[4:7], v[164:167], v[204:207], v[4:7]
	v_mfma_i32_16x16x64_i8 v[0:3], v[172:175], v[204:207], v[0:3]
	v_mfma_i32_16x16x64_i8 v[52:55], v[168:171], v[184:187], v[52:55]
	v_mfma_i32_16x16x64_i8 v[48:51], v[176:179], v[184:187], v[48:51]
	v_mfma_i32_16x16x64_i8 v[36:39], v[168:171], v[192:195], v[36:39]
	s_setprio 2
	s_barrier
	v_mfma_i32_16x16x64_i8 v[32:35], v[176:179], v[192:195], v[32:35]
	v_mfma_i32_16x16x64_i8 v[20:23], v[168:171], v[200:203], v[20:23]
	v_mfma_i32_16x16x64_i8 v[16:19], v[176:179], v[200:203], v[16:19]
	v_mfma_i32_16x16x64_i8 v[4:7], v[168:171], v[208:211], v[4:7]
	v_mfma_i32_16x16x64_i8 v[0:3], v[176:179], v[208:211], v[0:3]
	s_setprio 0
	s_add_i32 s80, 0, 0x18000
	s_add_i32 s81, 0, 0x1c000
	v_add_u32_e32 v160, s80, v152
	v_add_u32_e32 v176, s81, v152
	ds_read_b128 v[144:147], v160
	ds_read_b128 v[148:151], v160 offset:1024
	ds_read_b128 v[156:159], v160 offset:2048
	ds_read_b128 v[160:163], v160 offset:3072
	ds_read_b128 v[164:167], v176
	ds_read_b128 v[168:171], v176 offset:1024
	ds_read_b128 v[172:175], v176 offset:2048
	ds_read_b128 v[176:179], v176 offset:3072
	s_add_u32 s58, s58, 0x80000
	s_addc_u32 s59, s59, 0
	s_mov_b32 m0, s53
	v_lshl_add_u64 v[220:221], s[58:59], 0, v[134:135]
	ds_read_b128 v[180:183], v155 offset:32768
	ds_read_b128 v[184:187], v155 offset:33792
	ds_read_b128 v[188:191], v155 offset:34816
	ds_read_b128 v[192:195], v155 offset:35840
	ds_read_b128 v[196:199], v155 offset:36864
	ds_read_b128 v[200:203], v155 offset:37888
	ds_read_b128 v[204:207], v155 offset:38912
	ds_read_b128 v[208:211], v155 offset:39936
	global_load_lds_dwordx4 v[220:221], off
	v_lshl_add_u64 v[220:221], s[58:59], 0, v[130:131]
	s_mov_b32 m0, s60
	s_nop 0
	global_load_lds_dwordx4 v[220:221], off
	s_waitcnt vmcnt(8)
	s_waitcnt lgkmcnt(0)
	s_barrier
	s_setprio 1
	v_mfma_i32_16x16x64_i8 v[124:127], v[144:147], v[180:183], v[124:127]
	v_mfma_i32_16x16x64_i8 v[120:123], v[156:159], v[180:183], v[120:123]
	v_mfma_i32_16x16x64_i8 v[108:111], v[144:147], v[188:191], v[108:111]
	v_mfma_i32_16x16x64_i8 v[104:107], v[156:159], v[188:191], v[104:107]
	v_mfma_i32_16x16x64_i8 v[92:95], v[144:147], v[196:199], v[92:95]
	v_mfma_i32_16x16x64_i8 v[88:91], v[156:159], v[196:199], v[88:91]
	v_mfma_i32_16x16x64_i8 v[76:79], v[144:147], v[204:207], v[76:79]
	v_mfma_i32_16x16x64_i8 v[72:75], v[156:159], v[204:207], v[72:75]
	v_mfma_i32_16x16x64_i8 v[124:127], v[148:151], v[184:187], v[124:127]
	v_mfma_i32_16x16x64_i8 v[120:123], v[160:163], v[184:187], v[120:123]
	v_mfma_i32_16x16x64_i8 v[108:111], v[148:151], v[192:195], v[108:111]
	v_mfma_i32_16x16x64_i8 v[104:107], v[160:163], v[192:195], v[104:107]
	v_mfma_i32_16x16x64_i8 v[92:95], v[148:151], v[200:203], v[92:95]
	v_mfma_i32_16x16x64_i8 v[88:91], v[160:163], v[200:203], v[88:91]
	v_mfma_i32_16x16x64_i8 v[76:79], v[148:151], v[208:211], v[76:79]
	v_mfma_i32_16x16x64_i8 v[72:75], v[160:163], v[208:211], v[72:75]
	s_setprio 0
	s_setprio 1
	v_mfma_i32_16x16x64_i8 v[116:119], v[164:167], v[180:183], v[116:119]
	v_mfma_i32_16x16x64_i8 v[112:115], v[172:175], v[180:183], v[112:115]
	v_mfma_i32_16x16x64_i8 v[100:103], v[164:167], v[188:191], v[100:103]
	v_mfma_i32_16x16x64_i8 v[96:99], v[172:175], v[188:191], v[96:99]
	v_mfma_i32_16x16x64_i8 v[84:87], v[164:167], v[196:199], v[84:87]
	v_mfma_i32_16x16x64_i8 v[80:83], v[172:175], v[196:199], v[80:83]
	v_mfma_i32_16x16x64_i8 v[68:71], v[164:167], v[204:207], v[68:71]
	v_mfma_i32_16x16x64_i8 v[64:67], v[172:175], v[204:207], v[64:67]
	v_mfma_i32_16x16x64_i8 v[116:119], v[168:171], v[184:187], v[116:119]
	v_mfma_i32_16x16x64_i8 v[112:115], v[176:179], v[184:187], v[112:115]
	v_mfma_i32_16x16x64_i8 v[100:103], v[168:171], v[192:195], v[100:103]
	s_setprio 2
	s_barrier
	v_mfma_i32_16x16x64_i8 v[96:99], v[176:179], v[192:195], v[96:99]
	v_mfma_i32_16x16x64_i8 v[84:87], v[168:171], v[200:203], v[84:87]
	v_mfma_i32_16x16x64_i8 v[80:83], v[176:179], v[200:203], v[80:83]
	v_mfma_i32_16x16x64_i8 v[68:71], v[168:171], v[208:211], v[68:71]
	v_mfma_i32_16x16x64_i8 v[64:67], v[176:179], v[208:211], v[64:67]
	s_setprio 0
	s_add_i32 s58, s80, s34
	v_lshl_add_u64 v[212:213], v[212:213], 0, s[26:27]
	s_mov_b32 m0, s58
	ds_read_b128 v[180:183], v155 offset:49152
	ds_read_b128 v[184:187], v155 offset:50176
	ds_read_b128 v[188:191], v155 offset:51200
	ds_read_b128 v[192:195], v155 offset:52224
	ds_read_b128 v[196:199], v155 offset:53248
	ds_read_b128 v[200:203], v155 offset:54272
	ds_read_b128 v[204:207], v155 offset:55296
	ds_read_b128 v[208:211], v155 offset:56320
	global_load_lds_dwordx4 v[212:213], off
	s_add_i32 m0, s58, 0x2000
	s_add_u32 s56, s56, 0x80080
	v_lshl_add_u64 v[212:213], v[214:215], 0, s[26:27]
	s_addc_u32 s57, s57, 0
	s_add_i32 s58, s81, s34
	global_load_lds_dwordx4 v[212:213], off
	v_lshl_add_u64 v[212:213], s[56:57], 0, v[132:133]
	s_mov_b32 m0, s58
	s_nop 0
	global_load_lds_dwordx4 v[212:213], off
	v_lshl_add_u64 v[212:213], s[56:57], 0, v[128:129]
	s_add_i32 m0, s58, 0x2000
	s_nop 0
	global_load_lds_dwordx4 v[212:213], off
	v_lshl_add_u64 v[212:213], v[216:217], 0, s[26:27]
	s_mov_b32 m0, s63
	s_nop 0
	global_load_lds_dwordx4 v[212:213], off
	v_lshl_add_u64 v[212:213], v[218:219], 0, s[26:27]
	s_mov_b32 m0, s70
	s_nop 0
	global_load_lds_dwordx4 v[212:213], off
	s_waitcnt vmcnt(8)
	s_waitcnt lgkmcnt(0)
	s_barrier
	s_setprio 1
	v_mfma_i32_16x16x64_i8 v[60:63], v[144:147], v[180:183], v[60:63]
	v_mfma_i32_16x16x64_i8 v[56:59], v[156:159], v[180:183], v[56:59]
	v_mfma_i32_16x16x64_i8 v[44:47], v[144:147], v[188:191], v[44:47]
	v_mfma_i32_16x16x64_i8 v[40:43], v[156:159], v[188:191], v[40:43]
	v_mfma_i32_16x16x64_i8 v[28:31], v[144:147], v[196:199], v[28:31]
	v_mfma_i32_16x16x64_i8 v[24:27], v[156:159], v[196:199], v[24:27]
	v_mfma_i32_16x16x64_i8 v[12:15], v[144:147], v[204:207], v[12:15]
	v_mfma_i32_16x16x64_i8 v[8:11], v[156:159], v[204:207], v[8:11]
	v_mfma_i32_16x16x64_i8 v[60:63], v[148:151], v[184:187], v[60:63]
	v_mfma_i32_16x16x64_i8 v[56:59], v[160:163], v[184:187], v[56:59]
	v_mfma_i32_16x16x64_i8 v[44:47], v[148:151], v[192:195], v[44:47]
	v_mfma_i32_16x16x64_i8 v[40:43], v[160:163], v[192:195], v[40:43]
	v_mfma_i32_16x16x64_i8 v[28:31], v[148:151], v[200:203], v[28:31]
	v_mfma_i32_16x16x64_i8 v[24:27], v[160:163], v[200:203], v[24:27]
	v_mfma_i32_16x16x64_i8 v[12:15], v[148:151], v[208:211], v[12:15]
	v_mfma_i32_16x16x64_i8 v[8:11], v[160:163], v[208:211], v[8:11]
	s_setprio 0
	s_setprio 1
	v_mfma_i32_16x16x64_i8 v[52:55], v[164:167], v[180:183], v[52:55]
	v_mfma_i32_16x16x64_i8 v[48:51], v[172:175], v[180:183], v[48:51]
	v_mfma_i32_16x16x64_i8 v[36:39], v[164:167], v[188:191], v[36:39]
	v_mfma_i32_16x16x64_i8 v[32:35], v[172:175], v[188:191], v[32:35]
	v_mfma_i32_16x16x64_i8 v[20:23], v[164:167], v[196:199], v[20:23]
	v_mfma_i32_16x16x64_i8 v[16:19], v[172:175], v[196:199], v[16:19]
	v_mfma_i32_16x16x64_i8 v[4:7], v[164:167], v[204:207], v[4:7]
	v_mfma_i32_16x16x64_i8 v[0:3], v[172:175], v[204:207], v[0:3]
	v_mfma_i32_16x16x64_i8 v[52:55], v[168:171], v[184:187], v[52:55]
	v_mfma_i32_16x16x64_i8 v[48:51], v[176:179], v[184:187], v[48:51]
	v_mfma_i32_16x16x64_i8 v[36:39], v[168:171], v[192:195], v[36:39]
	s_setprio 2
	s_barrier
	v_mfma_i32_16x16x64_i8 v[32:35], v[176:179], v[192:195], v[32:35]
	v_mfma_i32_16x16x64_i8 v[20:23], v[168:171], v[200:203], v[20:23]
	v_mfma_i32_16x16x64_i8 v[16:19], v[176:179], v[200:203], v[16:19]
	v_mfma_i32_16x16x64_i8 v[4:7], v[168:171], v[208:211], v[4:7]
	v_mfma_i32_16x16x64_i8 v[0:3], v[176:179], v[208:211], v[0:3]
	s_setprio 0
	s_add_i32 s79, s79, 2
	s_add_u32 s54, s54, 0x100
	s_addc_u32 s55, s55, 0
	s_add_u32 s77, s77, 0x100
	s_addc_u32 s78, s78, 0
	s_cmp_gt_u32 s79, 29
	s_cbranch_scc0 .LBB0_771

.LBB0_978:
	ds_read_b128 v[144:147], v153
	ds_read_b128 v[148:151], v153 offset:1024
	ds_read_b128 v[156:159], v153 offset:2048
	ds_read_b128 v[160:163], v153 offset:3072
	ds_read_b128 v[164:167], v154
	ds_read_b128 v[168:171], v154 offset:1024
	ds_read_b128 v[172:175], v154 offset:2048
	ds_read_b128 v[176:179], v154 offset:3072
	s_add_u32 s46, s40, 0x100
	s_addc_u32 s47, s41, 0
	s_cmpk_eq_i32 s77, 0x52
	s_cselect_b32 s51, s9, s47
	s_cselect_b32 s50, s8, s46
	s_cselect_b32 s49, s39, s76
	s_cselect_b32 s48, s38, s75
	v_lshl_add_u64 v[212:213], s[40:41], 0, v[136:137]
	s_add_i32 m0, s52, 0xc000
	ds_read_b128 v[180:183], v155
	ds_read_b128 v[184:187], v155 offset:1024
	ds_read_b128 v[188:191], v155 offset:2048
	ds_read_b128 v[192:195], v155 offset:3072
	ds_read_b128 v[196:199], v155 offset:4096
	ds_read_b128 v[200:203], v155 offset:5120
	ds_read_b128 v[204:207], v155 offset:6144
	ds_read_b128 v[208:211], v155 offset:7168
	global_load_lds_dwordx4 v[212:213], off
	v_lshl_add_u64 v[212:213], s[40:41], 0, v[138:139]
	s_add_i32 m0, s52, 0xe000
	s_nop 0
	global_load_lds_dwordx4 v[212:213], off
	s_waitcnt vmcnt(8)
	s_waitcnt lgkmcnt(0)
	s_barrier
	s_setprio 1
	v_mfma_i32_16x16x64_i8 v[124:127], v[144:147], v[180:183], v[124:127]
	v_mfma_i32_16x16x64_i8 v[120:123], v[156:159], v[180:183], v[120:123]
	v_mfma_i32_16x16x64_i8 v[108:111], v[144:147], v[188:191], v[108:111]
	v_mfma_i32_16x16x64_i8 v[104:107], v[156:159], v[188:191], v[104:107]
	v_mfma_i32_16x16x64_i8 v[92:95], v[144:147], v[196:199], v[92:95]
	v_mfma_i32_16x16x64_i8 v[88:91], v[156:159], v[196:199], v[88:91]
	v_mfma_i32_16x16x64_i8 v[76:79], v[144:147], v[204:207], v[76:79]
	v_mfma_i32_16x16x64_i8 v[72:75], v[156:159], v[204:207], v[72:75]
	v_mfma_i32_16x16x64_i8 v[124:127], v[148:151], v[184:187], v[124:127]
	v_mfma_i32_16x16x64_i8 v[120:123], v[160:163], v[184:187], v[120:123]
	v_mfma_i32_16x16x64_i8 v[108:111], v[148:151], v[192:195], v[108:111]
	v_mfma_i32_16x16x64_i8 v[104:107], v[160:163], v[192:195], v[104:107]
	v_mfma_i32_16x16x64_i8 v[92:95], v[148:151], v[200:203], v[92:95]
	v_mfma_i32_16x16x64_i8 v[88:91], v[160:163], v[200:203], v[88:91]
	v_mfma_i32_16x16x64_i8 v[76:79], v[148:151], v[208:211], v[76:79]
	v_mfma_i32_16x16x64_i8 v[72:75], v[160:163], v[208:211], v[72:75]
	s_setprio 0
	s_setprio 1
	v_mfma_i32_16x16x64_i8 v[116:119], v[164:167], v[180:183], v[116:119]
	v_mfma_i32_16x16x64_i8 v[112:115], v[172:175], v[180:183], v[112:115]
	v_mfma_i32_16x16x64_i8 v[100:103], v[164:167], v[188:191], v[100:103]
	v_mfma_i32_16x16x64_i8 v[96:99], v[172:175], v[188:191], v[96:99]
	v_mfma_i32_16x16x64_i8 v[84:87], v[164:167], v[196:199], v[84:87]
	v_mfma_i32_16x16x64_i8 v[80:83], v[172:175], v[196:199], v[80:83]
	v_mfma_i32_16x16x64_i8 v[68:71], v[164:167], v[204:207], v[68:71]
	v_mfma_i32_16x16x64_i8 v[64:67], v[172:175], v[204:207], v[64:67]
	v_mfma_i32_16x16x64_i8 v[116:119], v[168:171], v[184:187], v[116:119]
	v_mfma_i32_16x16x64_i8 v[112:115], v[176:179], v[184:187], v[112:115]
	v_mfma_i32_16x16x64_i8 v[100:103], v[168:171], v[192:195], v[100:103]
	v_mfma_i32_16x16x64_i8 v[96:99], v[176:179], v[192:195], v[96:99]
	s_setprio 2
	s_barrier
	v_mfma_i32_16x16x64_i8 v[84:87], v[168:171], v[200:203], v[84:87]
	v_mfma_i32_16x16x64_i8 v[80:83], v[176:179], v[200:203], v[80:83]
	v_mfma_i32_16x16x64_i8 v[68:71], v[168:171], v[208:211], v[68:71]
	v_mfma_i32_16x16x64_i8 v[64:67], v[176:179], v[208:211], v[64:67]
	s_setprio 0
	s_add_i32 s40, s61, s35
	v_lshl_add_u64 v[212:213], s[48:49], 0, v[132:133]
	s_mov_b32 m0, s40
	ds_read_b128 v[180:183], v155 offset:16384
	ds_read_b128 v[184:187], v155 offset:17408
	ds_read_b128 v[188:191], v155 offset:18432
	ds_read_b128 v[192:195], v155 offset:19456
	ds_read_b128 v[196:199], v155 offset:20480
	ds_read_b128 v[200:203], v155 offset:21504
	ds_read_b128 v[204:207], v155 offset:22528
	ds_read_b128 v[208:211], v155 offset:23552
	global_load_lds_dwordx4 v[212:213], off
	s_add_i32 m0, s40, 0x2000
	s_add_u32 s40, s48, 0x158000
	v_lshl_add_u64 v[214:215], s[48:49], 0, v[128:129]
	s_addc_u32 s41, s49, 0
	s_add_i32 s78, s62, s35
	global_load_lds_dwordx4 v[214:215], off
	v_lshl_add_u64 v[216:217], s[40:41], 0, v[132:133]
	s_mov_b32 m0, s78
	v_lshl_add_u64 v[218:219], s[50:51], 0, v[130:131]
	global_load_lds_dwordx4 v[216:217], off
	v_lshl_add_u64 v[216:217], s[40:41], 0, v[128:129]
	s_add_i32 m0, s78, 0x2000
	s_nop 0
	global_load_lds_dwordx4 v[216:217], off
	v_lshl_add_u64 v[216:217], s[50:51], 0, v[134:135]
	s_mov_b32 m0, s52
	s_nop 0
	global_load_lds_dwordx4 v[216:217], off
	s_mov_b32 m0, s53
	s_nop 0
	global_load_lds_dwordx4 v[218:219], off
	s_waitcnt vmcnt(8)
	s_waitcnt lgkmcnt(0)
	s_barrier
	s_setprio 1
	v_mfma_i32_16x16x64_i8 v[60:63], v[144:147], v[180:183], v[60:63]
	v_mfma_i32_16x16x64_i8 v[56:59], v[156:159], v[180:183], v[56:59]
	v_mfma_i32_16x16x64_i8 v[44:47], v[144:147], v[188:191], v[44:47]
	v_mfma_i32_16x16x64_i8 v[40:43], v[156:159], v[188:191], v[40:43]
	v_mfma_i32_16x16x64_i8 v[28:31], v[144:147], v[196:199], v[28:31]
	v_mfma_i32_16x16x64_i8 v[24:27], v[156:159], v[196:199], v[24:27]
	v_mfma_i32_16x16x64_i8 v[12:15], v[144:147], v[204:207], v[12:15]
	v_mfma_i32_16x16x64_i8 v[8:11], v[156:159], v[204:207], v[8:11]
	v_mfma_i32_16x16x64_i8 v[60:63], v[148:151], v[184:187], v[60:63]
	v_mfma_i32_16x16x64_i8 v[56:59], v[160:163], v[184:187], v[56:59]
	v_mfma_i32_16x16x64_i8 v[44:47], v[148:151], v[192:195], v[44:47]
	v_mfma_i32_16x16x64_i8 v[40:43], v[160:163], v[192:195], v[40:43]
	v_mfma_i32_16x16x64_i8 v[28:31], v[148:151], v[200:203], v[28:31]
	v_mfma_i32_16x16x64_i8 v[24:27], v[160:163], v[200:203], v[24:27]
	v_mfma_i32_16x16x64_i8 v[12:15], v[148:151], v[208:211], v[12:15]
	v_mfma_i32_16x16x64_i8 v[8:11], v[160:163], v[208:211], v[8:11]
	s_setprio 0
	s_setprio 1
	v_mfma_i32_16x16x64_i8 v[52:55], v[164:167], v[180:183], v[52:55]
	v_mfma_i32_16x16x64_i8 v[48:51], v[172:175], v[180:183], v[48:51]
	v_mfma_i32_16x16x64_i8 v[36:39], v[164:167], v[188:191], v[36:39]
	v_mfma_i32_16x16x64_i8 v[32:35], v[172:175], v[188:191], v[32:35]
	v_mfma_i32_16x16x64_i8 v[20:23], v[164:167], v[196:199], v[20:23]
	v_mfma_i32_16x16x64_i8 v[16:19], v[172:175], v[196:199], v[16:19]
	v_mfma_i32_16x16x64_i8 v[4:7], v[164:167], v[204:207], v[4:7]
	v_mfma_i32_16x16x64_i8 v[0:3], v[172:175], v[204:207], v[0:3]
	v_mfma_i32_16x16x64_i8 v[52:55], v[168:171], v[184:187], v[52:55]
	v_mfma_i32_16x16x64_i8 v[48:51], v[176:179], v[184:187], v[48:51]
	v_mfma_i32_16x16x64_i8 v[36:39], v[168:171], v[192:195], v[36:39]
	v_mfma_i32_16x16x64_i8 v[32:35], v[176:179], v[192:195], v[32:35]
	s_setprio 2
	s_barrier
	v_mfma_i32_16x16x64_i8 v[20:23], v[168:171], v[200:203], v[20:23]
	v_mfma_i32_16x16x64_i8 v[16:19], v[176:179], v[200:203], v[16:19]
	v_mfma_i32_16x16x64_i8 v[4:7], v[168:171], v[208:211], v[4:7]
	v_mfma_i32_16x16x64_i8 v[0:3], v[176:179], v[208:211], v[0:3]
	s_setprio 0
	s_add_i32 s78, 0, 0x18000
	s_add_i32 s79, 0, 0x1c000
	v_add_u32_e32 v160, s78, v152
	v_add_u32_e32 v176, s79, v152
	ds_read_b128 v[144:147], v160
	ds_read_b128 v[148:151], v160 offset:1024
	ds_read_b128 v[156:159], v160 offset:2048
	ds_read_b128 v[160:163], v160 offset:3072
	ds_read_b128 v[164:167], v176
	ds_read_b128 v[168:171], v176 offset:1024
	ds_read_b128 v[172:175], v176 offset:2048
	ds_read_b128 v[176:179], v176 offset:3072
	s_add_u32 s40, s50, 0x158000
	s_addc_u32 s41, s51, 0
	s_mov_b32 m0, s54
	v_lshl_add_u64 v[220:221], s[40:41], 0, v[134:135]
	ds_read_b128 v[180:183], v155 offset:32768
	ds_read_b128 v[184:187], v155 offset:33792
	ds_read_b128 v[188:191], v155 offset:34816
	ds_read_b128 v[192:195], v155 offset:35840
	ds_read_b128 v[196:199], v155 offset:36864
	ds_read_b128 v[200:203], v155 offset:37888
	ds_read_b128 v[204:207], v155 offset:38912
	ds_read_b128 v[208:211], v155 offset:39936
	global_load_lds_dwordx4 v[220:221], off
	v_lshl_add_u64 v[220:221], s[40:41], 0, v[130:131]
	s_mov_b32 m0, s55
	s_nop 0
	global_load_lds_dwordx4 v[220:221], off
	s_waitcnt vmcnt(8)
	s_waitcnt lgkmcnt(0)
	s_barrier
	s_setprio 1
	v_mfma_i32_16x16x64_i8 v[124:127], v[144:147], v[180:183], v[124:127]
	v_mfma_i32_16x16x64_i8 v[120:123], v[156:159], v[180:183], v[120:123]
	v_mfma_i32_16x16x64_i8 v[108:111], v[144:147], v[188:191], v[108:111]
	v_mfma_i32_16x16x64_i8 v[104:107], v[156:159], v[188:191], v[104:107]
	v_mfma_i32_16x16x64_i8 v[92:95], v[144:147], v[196:199], v[92:95]
	v_mfma_i32_16x16x64_i8 v[88:91], v[156:159], v[196:199], v[88:91]
	v_mfma_i32_16x16x64_i8 v[76:79], v[144:147], v[204:207], v[76:79]
	v_mfma_i32_16x16x64_i8 v[72:75], v[156:159], v[204:207], v[72:75]
	v_mfma_i32_16x16x64_i8 v[124:127], v[148:151], v[184:187], v[124:127]
	v_mfma_i32_16x16x64_i8 v[120:123], v[160:163], v[184:187], v[120:123]
	v_mfma_i32_16x16x64_i8 v[108:111], v[148:151], v[192:195], v[108:111]
	v_mfma_i32_16x16x64_i8 v[104:107], v[160:163], v[192:195], v[104:107]
	v_mfma_i32_16x16x64_i8 v[92:95], v[148:151], v[200:203], v[92:95]
	v_mfma_i32_16x16x64_i8 v[88:91], v[160:163], v[200:203], v[88:91]
	v_mfma_i32_16x16x64_i8 v[76:79], v[148:151], v[208:211], v[76:79]
	v_mfma_i32_16x16x64_i8 v[72:75], v[160:163], v[208:211], v[72:75]
	s_setprio 0
	s_setprio 1
	v_mfma_i32_16x16x64_i8 v[116:119], v[164:167], v[180:183], v[116:119]
	v_mfma_i32_16x16x64_i8 v[112:115], v[172:175], v[180:183], v[112:115]
	v_mfma_i32_16x16x64_i8 v[100:103], v[164:167], v[188:191], v[100:103]
	v_mfma_i32_16x16x64_i8 v[96:99], v[172:175], v[188:191], v[96:99]
	v_mfma_i32_16x16x64_i8 v[84:87], v[164:167], v[196:199], v[84:87]
	v_mfma_i32_16x16x64_i8 v[80:83], v[172:175], v[196:199], v[80:83]
	v_mfma_i32_16x16x64_i8 v[68:71], v[164:167], v[204:207], v[68:71]
	v_mfma_i32_16x16x64_i8 v[64:67], v[172:175], v[204:207], v[64:67]
	v_mfma_i32_16x16x64_i8 v[116:119], v[168:171], v[184:187], v[116:119]
	v_mfma_i32_16x16x64_i8 v[112:115], v[176:179], v[184:187], v[112:115]
	v_mfma_i32_16x16x64_i8 v[100:103], v[168:171], v[192:195], v[100:103]
	v_mfma_i32_16x16x64_i8 v[96:99], v[176:179], v[192:195], v[96:99]
	s_setprio 2
	s_barrier
	v_mfma_i32_16x16x64_i8 v[84:87], v[168:171], v[200:203], v[84:87]
	v_mfma_i32_16x16x64_i8 v[80:83], v[176:179], v[200:203], v[80:83]
	v_mfma_i32_16x16x64_i8 v[68:71], v[168:171], v[208:211], v[68:71]
	v_mfma_i32_16x16x64_i8 v[64:67], v[176:179], v[208:211], v[64:67]
	s_setprio 0
	s_add_i32 s40, s78, s35
	v_lshl_add_u64 v[212:213], v[212:213], 0, s[20:21]
	s_mov_b32 m0, s40
	ds_read_b128 v[180:183], v155 offset:49152
	ds_read_b128 v[184:187], v155 offset:50176
	ds_read_b128 v[188:191], v155 offset:51200
	ds_read_b128 v[192:195], v155 offset:52224
	ds_read_b128 v[196:199], v155 offset:53248
	ds_read_b128 v[200:203], v155 offset:54272
	ds_read_b128 v[204:207], v155 offset:55296
	ds_read_b128 v[208:211], v155 offset:56320
	global_load_lds_dwordx4 v[212:213], off
	s_add_i32 m0, s40, 0x2000
	s_add_u32 s40, s48, 0x158080
	v_lshl_add_u64 v[212:213], v[214:215], 0, s[20:21]
	s_addc_u32 s41, s49, 0
	s_add_i32 s48, s79, s35
	global_load_lds_dwordx4 v[212:213], off
	v_lshl_add_u64 v[212:213], s[40:41], 0, v[132:133]
	s_mov_b32 m0, s48
	s_nop 0
	global_load_lds_dwordx4 v[212:213], off
	v_lshl_add_u64 v[212:213], s[40:41], 0, v[128:129]
	s_add_i32 m0, s48, 0x2000
	s_nop 0
	global_load_lds_dwordx4 v[212:213], off
	v_lshl_add_u64 v[212:213], v[216:217], 0, s[20:21]
	s_mov_b32 m0, s58
	s_nop 0
	global_load_lds_dwordx4 v[212:213], off
	v_lshl_add_u64 v[212:213], v[218:219], 0, s[20:21]
	s_mov_b32 m0, s59
	s_nop 0
	global_load_lds_dwordx4 v[212:213], off
	s_waitcnt vmcnt(8)
	s_waitcnt lgkmcnt(0)
	s_barrier
	s_setprio 1
	v_mfma_i32_16x16x64_i8 v[60:63], v[144:147], v[180:183], v[60:63]
	v_mfma_i32_16x16x64_i8 v[56:59], v[156:159], v[180:183], v[56:59]
	v_mfma_i32_16x16x64_i8 v[44:47], v[144:147], v[188:191], v[44:47]
	v_mfma_i32_16x16x64_i8 v[40:43], v[156:159], v[188:191], v[40:43]
	v_mfma_i32_16x16x64_i8 v[28:31], v[144:147], v[196:199], v[28:31]
	v_mfma_i32_16x16x64_i8 v[24:27], v[156:159], v[196:199], v[24:27]
	v_mfma_i32_16x16x64_i8 v[12:15], v[144:147], v[204:207], v[12:15]
	v_mfma_i32_16x16x64_i8 v[8:11], v[156:159], v[204:207], v[8:11]
	v_mfma_i32_16x16x64_i8 v[60:63], v[148:151], v[184:187], v[60:63]
	v_mfma_i32_16x16x64_i8 v[56:59], v[160:163], v[184:187], v[56:59]
	v_mfma_i32_16x16x64_i8 v[44:47], v[148:151], v[192:195], v[44:47]
	v_mfma_i32_16x16x64_i8 v[40:43], v[160:163], v[192:195], v[40:43]
	v_mfma_i32_16x16x64_i8 v[28:31], v[148:151], v[200:203], v[28:31]
	v_mfma_i32_16x16x64_i8 v[24:27], v[160:163], v[200:203], v[24:27]
	v_mfma_i32_16x16x64_i8 v[12:15], v[148:151], v[208:211], v[12:15]
	v_mfma_i32_16x16x64_i8 v[8:11], v[160:163], v[208:211], v[8:11]
	s_setprio 0
	s_setprio 1
	v_mfma_i32_16x16x64_i8 v[52:55], v[164:167], v[180:183], v[52:55]
	v_mfma_i32_16x16x64_i8 v[48:51], v[172:175], v[180:183], v[48:51]
	v_mfma_i32_16x16x64_i8 v[36:39], v[164:167], v[188:191], v[36:39]
	v_mfma_i32_16x16x64_i8 v[32:35], v[172:175], v[188:191], v[32:35]
	v_mfma_i32_16x16x64_i8 v[20:23], v[164:167], v[196:199], v[20:23]
	v_mfma_i32_16x16x64_i8 v[16:19], v[172:175], v[196:199], v[16:19]
	v_mfma_i32_16x16x64_i8 v[4:7], v[164:167], v[204:207], v[4:7]
	v_mfma_i32_16x16x64_i8 v[0:3], v[172:175], v[204:207], v[0:3]
	v_mfma_i32_16x16x64_i8 v[52:55], v[168:171], v[184:187], v[52:55]
	v_mfma_i32_16x16x64_i8 v[48:51], v[176:179], v[184:187], v[48:51]
	v_mfma_i32_16x16x64_i8 v[36:39], v[168:171], v[192:195], v[36:39]
	v_mfma_i32_16x16x64_i8 v[32:35], v[176:179], v[192:195], v[32:35]
	s_setprio 2
	s_barrier
	v_mfma_i32_16x16x64_i8 v[20:23], v[168:171], v[200:203], v[20:23]
	v_mfma_i32_16x16x64_i8 v[16:19], v[176:179], v[200:203], v[16:19]
	v_mfma_i32_16x16x64_i8 v[4:7], v[168:171], v[208:211], v[4:7]
	v_mfma_i32_16x16x64_i8 v[0:3], v[176:179], v[208:211], v[0:3]
	s_setprio 0
	s_add_i32 s77, s77, 2
	s_add_u32 s75, s75, 0x100
	s_addc_u32 s76, s76, 0
	s_cmpk_gt_u32 s77, 0x53
	s_mov_b64 s[40:41], s[46:47]
	s_cbranch_scc0 .LBB0_978
